# nt hint also on the SSD conv phase output stores
# baseline (speedup 1.0000x reference)
; DI int get_tid() { int t = threadIdx.x; asm volatile("" : "+v"(t)); return t; }
; DI int get_bid() { int t = blockIdx.x; asm volatile("" : "+s"(t)); return t; }
; DI U4 pack8(const float (&x)[8]) { return mku4(pack2(x[0], x[1]), pack2(x[2], x[3]), pack2(x[4], x[5]), pack2(x[6], x[7])); }
; DI float siluf(float x) { return x / (1.f + __expf(-x)); }
; DI void ssd_conv8(const u16* zx, int row, int lo, int hi, int ch0, const float* cw, const float* cb, float (&out)[8]) {
;     ...
;   for (int e = 0; e < 8; ++e) out[e] = siluf(acc[e]);
; }
; DI float softplusf(float x) { return x > 20.f ? x : log1pf(__expf(x)); }
; DI float wave_incl_scan(float v) {
;   const int lane = get_tid() & 63;
;   for (int o = 1; o < 64; o <<= 1) { float u = __shfl_up(v, o); if (lane >= o) v += u; }
;   return v;
; }
; DI void phase_ssdconv(PP p, int l) {
;   const u16* zx = (const u16*)(p->ws + A_SSDZX);
;   u16* xs = (u16*)(p->ws + A_XSACT); u16* bc = (u16*)(p->ws + A_BCACT);
;   const float* cw = p->in[I_SCW] + (size_t)l * 5 * 1024; const float* cb = p->in[I_SCB] + l * 1024;
;   const int total = ROWS * 128;
;   for (int i = get_bid() * 256 + get_tid(); i < total; i += gridDim.x * 256) {
;     const int row = i >> 7, ch0 = (i & 127) * 8;
;     const int b = row / TT, t = row - b * TT;
;     const int lo = t < CTX ? b * TT : b * TT + CTX, hi = t < CTX ? b * TT + CTX : (b + 1) * TT;
;     float v[8];
;     ssd_conv8(zx, row, lo, hi, ch0, cw, cb, v);
;     u16* dst = ch0 < 512 ? xs + (size_t)row * 512 + ch0 : bc + (size_t)row * 512 + (ch0 - 512);
;     *(U4*)dst = pack8(v);
.Lsc_skip4:
	v_mul_f32_e32 v174, 0xbfb8aa3b, v24
	v_mul_f32_e32 v175, 0xbfb8aa3b, v25
	v_exp_f32_e32 v174, v174
	v_exp_f32_e32 v175, v175
	s_nop 0
	v_pk_add_f32 v[174:175], v[174:175], 1.0 op_sel_hi:[1,0]
	s_nop 0
	v_div_scale_f32 v196, s[12:13], v174, v174, v24
	v_rcp_f32_e32 v197, v196
	s_nop 0
	v_fma_f32 v170, -v196, v197, 1.0
	v_fmac_f32_e32 v197, v170, v197
	v_div_scale_f32 v171, vcc, v24, v174, v24
	v_mul_f32_e32 v172, v171, v197
	v_fma_f32 v170, -v196, v172, v171
	v_fmac_f32_e32 v172, v170, v197
	v_fma_f32 v196, -v196, v172, v171
	v_div_fmas_f32 v196, v196, v197, v172
	v_div_fixup_f32 v176, v196, v174, v24
	v_div_scale_f32 v196, s[12:13], v175, v175, v25
	v_rcp_f32_e32 v197, v196
	s_nop 0
	v_fma_f32 v170, -v196, v197, 1.0
	v_fmac_f32_e32 v197, v170, v197
	v_div_scale_f32 v171, vcc, v25, v175, v25
	v_mul_f32_e32 v172, v171, v197
	v_fma_f32 v170, -v196, v172, v171
	v_fmac_f32_e32 v172, v170, v197
	v_fma_f32 v196, -v196, v172, v171
	v_div_fmas_f32 v196, v196, v197, v172
	v_div_fixup_f32 v177, v196, v175, v25
	v_mul_f32_e32 v174, 0xbfb8aa3b, v26
	v_mul_f32_e32 v175, 0xbfb8aa3b, v27
	v_exp_f32_e32 v174, v174
	v_exp_f32_e32 v175, v175
	s_nop 0
	v_pk_add_f32 v[174:175], v[174:175], 1.0 op_sel_hi:[1,0]
	s_nop 0
	v_div_scale_f32 v196, s[12:13], v174, v174, v26
	v_rcp_f32_e32 v197, v196
	s_nop 0
	v_fma_f32 v170, -v196, v197, 1.0
	v_fmac_f32_e32 v197, v170, v197
	v_div_scale_f32 v171, vcc, v26, v174, v26
	v_mul_f32_e32 v172, v171, v197
	v_fma_f32 v170, -v196, v172, v171
	v_fmac_f32_e32 v172, v170, v197
	v_fma_f32 v196, -v196, v172, v171
	v_div_fmas_f32 v196, v196, v197, v172
	v_div_fixup_f32 v178, v196, v174, v26
	v_div_scale_f32 v196, s[12:13], v175, v175, v27
	v_rcp_f32_e32 v197, v196
	s_nop 0
	v_fma_f32 v170, -v196, v197, 1.0
	v_fmac_f32_e32 v197, v170, v197
	v_div_scale_f32 v171, vcc, v27, v175, v27
	v_mul_f32_e32 v172, v171, v197
	v_fma_f32 v170, -v196, v172, v171
	v_fmac_f32_e32 v172, v170, v197
	v_fma_f32 v196, -v196, v172, v171
	v_div_fmas_f32 v196, v196, v197, v172
	v_div_fixup_f32 v179, v196, v175, v27
	v_mul_f32_e32 v174, 0xbfb8aa3b, v28
	v_mul_f32_e32 v175, 0xbfb8aa3b, v29
	v_exp_f32_e32 v174, v174
	v_exp_f32_e32 v175, v175
	s_nop 0
	v_pk_add_f32 v[174:175], v[174:175], 1.0 op_sel_hi:[1,0]
	s_nop 0
	v_div_scale_f32 v196, s[12:13], v174, v174, v28
	v_rcp_f32_e32 v197, v196
	s_nop 0
	v_fma_f32 v170, -v196, v197, 1.0
	v_fmac_f32_e32 v197, v170, v197
	v_div_scale_f32 v171, vcc, v28, v174, v28
	v_mul_f32_e32 v172, v171, v197
	v_fma_f32 v170, -v196, v172, v171
	v_fmac_f32_e32 v172, v170, v197
	v_fma_f32 v196, -v196, v172, v171
	v_div_fmas_f32 v196, v196, v197, v172
	v_div_fixup_f32 v180, v196, v174, v28
	v_div_scale_f32 v196, s[12:13], v175, v175, v29
	v_rcp_f32_e32 v197, v196
	s_nop 0
	v_fma_f32 v170, -v196, v197, 1.0
	v_fmac_f32_e32 v197, v170, v197
	v_div_scale_f32 v171, vcc, v29, v175, v29
	v_mul_f32_e32 v172, v171, v197
	v_fma_f32 v170, -v196, v172, v171
	v_fmac_f32_e32 v172, v170, v197
	v_fma_f32 v196, -v196, v172, v171
	v_div_fmas_f32 v196, v196, v197, v172
	v_div_fixup_f32 v181, v196, v175, v29
	v_mul_f32_e32 v174, 0xbfb8aa3b, v30
	v_mul_f32_e32 v175, 0xbfb8aa3b, v31
	v_exp_f32_e32 v174, v174
	v_exp_f32_e32 v175, v175
	s_nop 0
	v_pk_add_f32 v[174:175], v[174:175], 1.0 op_sel_hi:[1,0]
	s_nop 0
	v_div_scale_f32 v196, s[12:13], v174, v174, v30
	v_rcp_f32_e32 v197, v196
	s_nop 0
	v_fma_f32 v170, -v196, v197, 1.0
	v_fmac_f32_e32 v197, v170, v197
	v_div_scale_f32 v171, vcc, v30, v174, v30
	v_mul_f32_e32 v172, v171, v197
	v_fma_f32 v170, -v196, v172, v171
	v_fmac_f32_e32 v172, v170, v197
	v_fma_f32 v196, -v196, v172, v171
	v_div_fmas_f32 v196, v196, v197, v172
	v_div_fixup_f32 v182, v196, v174, v30
	v_div_scale_f32 v196, s[12:13], v175, v175, v31
	v_rcp_f32_e32 v197, v196
	s_nop 0
	v_fma_f32 v170, -v196, v197, 1.0
	v_fmac_f32_e32 v197, v170, v197
	v_div_scale_f32 v171, vcc, v31, v175, v31
	v_mul_f32_e32 v172, v171, v197
	v_fma_f32 v170, -v196, v172, v171
	v_fmac_f32_e32 v172, v170, v197
	v_fma_f32 v196, -v196, v172, v171
	v_div_fmas_f32 v196, v196, v197, v172
	v_div_fixup_f32 v183, v196, v175, v31
	v_cvt_pk_bf16_f32 v188, v176, v177
	v_cvt_pk_bf16_f32 v189, v178, v179
	v_cvt_pk_bf16_f32 v190, v180, v181
	v_cvt_pk_bf16_f32 v191, v182, v183
	s_lshl_b32 s12, s0, 10
	v_add_u32_e32 v0, s12, v3
	global_store_dwordx4 v0, v[188:191], s[10:11] nt
	s_waitcnt vmcnt(1)
	s_cmp_eq_u32 s14, 1
	s_cbranch_scc1 .Lsc_done
	s_mov_b32 s0, s1
	s_branch .Lsc_loop
